# stack: prep W-transpose loads de-serialized + POST mini-GEMM loads hoisted + DSA per-query epilogue spread over 64 lanes via LDS
# speedup vs baseline: 1.0149x; 1.0149x over previous
; #define LAS __attribute__((address_space(3)))
; DI u16 f2bf(float f) { return (u16)(pk2(f, 0.f) & 0xffffu); }
; template <int MAP> DI void wtile(LAS float* T, const float* src, int ld_src, const float* g, u16* dst, int Kdim, int n0, int k0) {
;     ...
;   __syncthreads();
; #pragma unroll
;   for (int i = 0; i < 8; ++i) { const int idx = tid + 512 * i, nn = idx >> 6, kk = idx & 63; dst[(size_t)(n0 + nn) * Kdim + k0 + kk] = f2bf(T[nn * 65 + kk]); }
;   __syncthreads();
; }
; DI void prep_weights(const Params& p, LAS unsigned char* lds) {
;   LAS float* T = (LAS float*)lds;
;   constexpr int U_IN = (NP / 64) * (DM / 64), U_OUT = (DM / 64) * (DM / 64), U_KV = 4, U_L = U_IN + U_OUT + U_KV;
;   for (int u = blockIdx.x; u < 2 * U_L; u += gridDim.x) {
;     const int l = u / U_L; int r = u % U_L;
;     if (r < U_IN) { wtile<1>(T, p.w_in + (size_t)l * DM * DIN, DIN, p.norm_g + l * DM, (u16*)(p.ws + WS_WIN) + (size_t)l * NP * DM, DM, (r / 16) * 64, (r % 16) * 64); }
.LBB0_2:
	s_or_b64 exec, exec, s[0:1]
	s_load_dwordx16 s[12:27], s[10:11], 0x0
	s_cmpk_gt_i32 s42, 0xa87
	s_waitcnt lgkmcnt(0)
	v_writelane_b32 v252, s12, 7
	s_nop 1
	v_writelane_b32 v252, s13, 8
	v_writelane_b32 v252, s14, 9
	v_writelane_b32 v252, s15, 10
	v_writelane_b32 v252, s16, 11
	v_writelane_b32 v252, s17, 12
	v_writelane_b32 v252, s18, 13
	v_writelane_b32 v252, s19, 14
	v_writelane_b32 v252, s20, 15
	v_writelane_b32 v252, s21, 16
	v_writelane_b32 v252, s22, 17
	v_writelane_b32 v252, s23, 18
	v_writelane_b32 v252, s24, 19
	v_writelane_b32 v252, s25, 20
	v_writelane_b32 v252, s26, 21
	v_writelane_b32 v252, s27, 22
	s_cbranch_scc1 .LBB0_61
	s_load_dwordx16 s[44:59], s[10:11], 0x0
	s_add_u32 s22, s96, 0x1600000
	s_addc_u32 s23, s97, 0
	s_load_dword s5, s[10:11], 0x98
	v_mov_b32_e32 v3, 0
	s_waitcnt lgkmcnt(0)
	s_cmp_lg_u64 s[52:53], 0
	s_cselect_b64 s[0:1], -1, 0
	s_add_u32 s24, s96, 0x1200000
	s_addc_u32 s25, s97, 0
	s_add_u32 s26, s96, 0x100000
	s_addc_u32 s27, s97, 0
	s_cmp_lg_u64 s[48:49], 0
	s_cselect_b64 s[2:3], -1, 0
	s_lshl_b32 s4, s42, 2
	s_add_i32 s30, s4, 0x7fffef00
	s_lshl_b32 s4, s42, 5
	s_lshl_b32 s28, s42, 6
	s_lshl_b32 s29, s5, 6
	s_lshl_b32 s31, s5, 2
	s_add_i32 s33, s4, 0x7fff5800
	s_lshl_b32 s34, s5, 5
	v_cndmask_b32_e64 v1, 0, 1, s[0:1]
	s_movk_i32 s35, 0x104
	s_movk_i32 s36, 0x3c0
	s_movk_i32 s37, 0x10c8
	s_movk_i32 s38, 0x4320
	s_mov_b32 s39, s42
	s_branch .LBB0_7
.LBB0_5:
	s_or_b64 exec, exec, s[20:21]
	s_mul_i32 s5, s12, 0x880000
	s_mul_hi_i32 s4, s12, 0x880000
	s_add_u32 s6, s26, s5
	s_addc_u32 s7, s27, s4
	s_ashr_i32 s15, s14, 31
	s_lshl_b64 s[4:5], s[14:15], 1
	v_lshl_add_u32 v2, v11, 2, v12
	s_add_u32 s4, s6, s4
	ds_write_b32 v2, v4
	v_lshl_add_u32 v4, v10, 2, 0
	s_addc_u32 s5, s7, s5
	v_lshlrev_b32_e32 v2, 1, v10
	v_lshl_add_u64 v[16:17], s[4:5], 0, v[2:3]
	v_mad_u64_u32 v[18:19], s[4:5], v6, s35, v[4:5]
	v_mad_u64_u32 v[20:21], s[4:5], v7, s35, v[4:5]
	v_mad_u64_u32 v[22:23], s[4:5], v8, s35, v[4:5]
	v_mad_u64_u32 v[24:25], s[4:5], v9, s35, v[4:5]
	v_mad_u64_u32 v[26:27], s[4:5], v13, s35, v[4:5]
	v_mad_u64_u32 v[28:29], s[4:5], v14, s35, v[4:5]
	v_mad_u64_u32 v[30:31], s[4:5], v15, s35, v[4:5]
	v_mad_u64_u32 v[4:5], s[4:5], v11, s35, v[4:5]
	s_waitcnt lgkmcnt(0)
	s_barrier
	ds_read_b32 v2, v18
	ds_read_b32 v10, v20
	ds_read_b32 v12, v22
	ds_read_b32 v18, v24
	ds_read_b32 v19, v26
	ds_read_b32 v20, v28
	ds_read_b32 v21, v30
	ds_read_b32 v22, v4
	v_add_u32_e32 v4, s13, v6
	v_ashrrev_i32_e32 v5, 31, v4
	v_lshlrev_b64 v[4:5], 11, v[4:5]
	s_waitcnt lgkmcnt(7)
	v_cvt_pk_bf16_f32 v2, v2, s0
	v_lshl_add_u64 v[4:5], v[16:17], 0, v[4:5]
	global_store_short v[4:5], v2, off
	v_add_u32_e32 v4, s13, v7
	v_ashrrev_i32_e32 v5, 31, v4
	v_lshlrev_b64 v[4:5], 11, v[4:5]
	s_waitcnt lgkmcnt(6)
	v_cvt_pk_bf16_f32 v2, v10, s0
	v_lshl_add_u64 v[4:5], v[16:17], 0, v[4:5]
	global_store_short v[4:5], v2, off
	v_add_u32_e32 v4, s13, v8
	v_ashrrev_i32_e32 v5, 31, v4
	v_lshlrev_b64 v[4:5], 11, v[4:5]
	s_waitcnt lgkmcnt(5)
	v_cvt_pk_bf16_f32 v2, v12, s0
	v_lshl_add_u64 v[4:5], v[16:17], 0, v[4:5]
	global_store_short v[4:5], v2, off
	v_add_u32_e32 v4, s13, v9
	v_ashrrev_i32_e32 v5, 31, v4
	v_lshlrev_b64 v[4:5], 11, v[4:5]
	s_waitcnt lgkmcnt(4)
	v_cvt_pk_bf16_f32 v2, v18, s0
	v_lshl_add_u64 v[4:5], v[16:17], 0, v[4:5]
	global_store_short v[4:5], v2, off
	v_add_u32_e32 v4, s13, v13
	v_ashrrev_i32_e32 v5, 31, v4
	v_lshlrev_b64 v[4:5], 11, v[4:5]
	s_waitcnt lgkmcnt(3)
	v_cvt_pk_bf16_f32 v2, v19, s0
	v_lshl_add_u64 v[4:5], v[16:17], 0, v[4:5]
	global_store_short v[4:5], v2, off
	v_add_u32_e32 v4, s13, v14
	v_ashrrev_i32_e32 v5, 31, v4
	v_lshlrev_b64 v[4:5], 11, v[4:5]
	s_waitcnt lgkmcnt(2)
	v_cvt_pk_bf16_f32 v2, v20, s0
	v_lshl_add_u64 v[4:5], v[16:17], 0, v[4:5]
	global_store_short v[4:5], v2, off
	v_add_u32_e32 v4, s13, v15
	v_ashrrev_i32_e32 v5, 31, v4
	v_lshlrev_b64 v[4:5], 11, v[4:5]
	s_waitcnt lgkmcnt(1)
	v_cvt_pk_bf16_f32 v2, v21, s0
	v_lshl_add_u64 v[4:5], v[16:17], 0, v[4:5]
	global_store_short v[4:5], v2, off
	v_add_u32_e32 v4, s13, v11
	v_ashrrev_i32_e32 v5, 31, v4
	v_lshlrev_b64 v[4:5], 11, v[4:5]
	s_waitcnt lgkmcnt(0)
	v_cvt_pk_bf16_f32 v2, v22, s0
	v_lshl_add_u64 v[4:5], v[16:17], 0, v[4:5]
	global_store_short v[4:5], v2, off
	s_barrier

; template <int MAP> DI void wtile(LAS float* T, const float* src, int ld_src, const float* g, u16* dst, int Kdim, int n0, int k0) {
;     ...
;   for (int i = 0; i < 8; ++i) {
;     const int idx = tid + 512 * i, kk = idx >> 6, nn = idx & 63; int c = n0 + nn;
;     if (MAP == 1) { c = c < 960 ? c : (c < 4288 ? c + 8 : (c < 4296 ? 960 + (c - 4288) : -1)); }
;     float v = 0.f;
;     if (c >= 0) { v = src[(size_t)(k0 + kk) * ld_src + c]; if (g) v *= g[k0 + kk]; if (MAP == 1 && n0 + nn >= C_QD && n0 + nn < C_QD + 256) v *= LOG2E * 0.125f; }
;     T[nn * 65 + kk] = v;
;   }
.LBB0_29:
	s_andn2_b64 vcc, exec, s[4:5]
	s_cbranch_vccnz .LBB0_6
	s_load_dwordx16 s[44:59], s[10:11], 0x0
	s_mul_i32 s5, s12, 0x10c8000
	s_mul_hi_i32 s4, s12, 0x10c8000
	v_mov_b32_e32 v11, v168
	s_waitcnt lgkmcnt(0)
	s_add_u32 s18, s50, s5
	s_addc_u32 s19, s51, s4
	s_lshl_b32 s4, s12, 10
	s_ashr_i32 s5, s4, 31
	s_lshl_b64 s[4:5], s[4:5], 2
	s_add_u32 s16, s48, s4
	s_addc_u32 s17, s49, s5
	s_bfe_u32 s4, s8, 0x4001b
	s_add_i32 s4, s8, s4
	s_sext_i32_i16 s5, s4
	s_and_b32 s4, s4, 0xfff0
	s_sub_i32 s4, s8, s4
	s_lshl_b32 s5, s5, 2
	s_sext_i32_i16 s4, s4
	s_and_b32 s13, s5, 0xffffffc0
	s_lshl_b32 s14, s4, 6
	v_bfi_b32 v2, 63, v11, s5
	s_cmpk_lt_u32 s13, 0x10c0
	v_add_u32_e32 v4, 0xfffff300, v2
	v_cmp_gt_u32_e32 vcc, s37, v2
	v_add_u32_e32 v5, 8, v2
	v_ashrrev_i32_e32 v6, 6, v11
	v_cndmask_b32_e32 v4, -1, v4, vcc
	s_cselect_b64 vcc, -1, 0
	s_add_i32 s4, s13, 0xfffff340
	v_cndmask_b32_e32 v4, v4, v5, vcc
	v_cmp_gt_i32_e32 vcc, s36, v2
	s_cmpk_lt_u32 s4, 0x100
	v_cndmask_b32_e64 v5, 0, 1, s[2:3]
	v_cndmask_b32_e32 v2, v4, v2, vcc
	s_cselect_b64 s[8:9], -1, 0
	v_cmp_lt_i32_e64 s[6:7], -1, v2
	v_mov_b32_e32 v4, 0
	v_cmp_ne_u32_e64 s[4:5], 1, v5
	v_mov_b32_e32 v40, 0
	v_mov_b32_e32 v41, 0
	v_mov_b32_e32 v42, 0
	v_mov_b32_e32 v43, 0
	v_mov_b32_e32 v44, 0
	v_mov_b32_e32 v45, 0
	v_mov_b32_e32 v46, 0
	v_mov_b32_e32 v47, 0
	s_and_saveexec_b64 s[20:21], s[6:7]
	s_cbranch_execz .Lmy_prep_w
	v_add_u32_e32 v4, s14, v6
	v_mov_b64_e32 v[8:9], s[18:19]
	v_mad_i64_i32 v[8:9], s[40:41], v4, s38, v[8:9]
	s_mov_b32 s100, 0x21900
	s_mov_b32 s101, 0
	v_lshl_add_u64 v[8:9], v[2:3], 2, v[8:9]
	global_load_dword v40, v[8:9], off
	v_lshl_add_u64 v[8:9], v[8:9], 0, s[100:101]
	global_load_dword v41, v[8:9], off
	v_lshl_add_u64 v[8:9], v[8:9], 0, s[100:101]
	global_load_dword v42, v[8:9], off
	v_lshl_add_u64 v[8:9], v[8:9], 0, s[100:101]
	global_load_dword v43, v[8:9], off
	v_lshl_add_u64 v[8:9], v[8:9], 0, s[100:101]
	global_load_dword v44, v[8:9], off
	v_lshl_add_u64 v[8:9], v[8:9], 0, s[100:101]
	global_load_dword v45, v[8:9], off
	v_lshl_add_u64 v[8:9], v[8:9], 0, s[100:101]
	global_load_dword v46, v[8:9], off
	v_lshl_add_u64 v[8:9], v[8:9], 0, s[100:101]
	global_load_dword v47, v[8:9], off
	s_and_b64 vcc, exec, s[4:5]
	s_cbranch_vccnz .Lmy_prep_nog
	v_ashrrev_i32_e32 v5, 31, v4
	v_lshl_add_u64 v[4:5], v[4:5], 2, s[16:17]
	global_load_dword v48, v[4:5], off
	global_load_dword v49, v[4:5], off offset:32
	global_load_dword v50, v[4:5], off offset:64
	global_load_dword v51, v[4:5], off offset:96
	global_load_dword v52, v[4:5], off offset:128
	global_load_dword v53, v[4:5], off offset:160
	global_load_dword v54, v[4:5], off offset:192
	global_load_dword v55, v[4:5], off offset:224
	s_waitcnt vmcnt(0)
	v_mul_f32_e32 v40, v40, v48
	v_mul_f32_e32 v41, v41, v49
	v_mul_f32_e32 v42, v42, v50
	v_mul_f32_e32 v43, v43, v51
	v_mul_f32_e32 v44, v44, v52
	v_mul_f32_e32 v45, v45, v53
	v_mul_f32_e32 v46, v46, v54
	v_mul_f32_e32 v47, v47, v55
.Lmy_prep_nog:
	s_waitcnt vmcnt(0)
	v_mul_f32_e32 v48, 0x3e38aa3b, v40
	v_mul_f32_e32 v49, 0x3e38aa3b, v41
	v_mul_f32_e32 v50, 0x3e38aa3b, v42
	v_mul_f32_e32 v51, 0x3e38aa3b, v43
	v_mul_f32_e32 v52, 0x3e38aa3b, v44
	v_mul_f32_e32 v53, 0x3e38aa3b, v45
	v_mul_f32_e32 v54, 0x3e38aa3b, v46
	v_mul_f32_e32 v55, 0x3e38aa3b, v47
	v_cndmask_b32_e64 v40, v40, v48, s[8:9]
	v_cndmask_b32_e64 v41, v41, v49, s[8:9]
	v_cndmask_b32_e64 v42, v42, v50, s[8:9]
	v_cndmask_b32_e64 v43, v43, v51, s[8:9]
	v_cndmask_b32_e64 v44, v44, v52, s[8:9]
	v_cndmask_b32_e64 v45, v45, v53, s[8:9]
	v_cndmask_b32_e64 v46, v46, v54, s[8:9]
	v_cndmask_b32_e64 v47, v47, v55, s[8:9]
.Lmy_prep_w:
	s_or_b64 exec, exec, s[20:21]
	v_and_b32_e32 v10, 63, v11
	v_mad_u32_u24 v12, v10, s35, 0
	v_lshl_add_u32 v5, v6, 2, v12
	ds_write_b32 v5, v40
	ds_write_b32 v5, v41 offset:32
	ds_write_b32 v5, v42 offset:64
	ds_write_b32 v5, v43 offset:96
	ds_write_b32 v5, v44 offset:128
	ds_write_b32 v5, v45 offset:160
	ds_write_b32 v5, v46 offset:192
	v_mov_b32_e32 v4, v47
	v_add_u32_e32 v7, 8, v6
	v_add_u32_e32 v8, 16, v6
	v_add_u32_e32 v9, 24, v6
	v_add_u32_e32 v13, 32, v6
	v_add_u32_e32 v14, 40, v6
	v_add_u32_e32 v15, 48, v6
	v_add_u32_e32 v11, 56, v6
	s_branch .LBB0_5

; DI unsigned pk2(float lo, float hi) { f32x2 x = {lo, hi}; return __builtin_bit_cast(unsigned, __builtin_convertvector(x, bf16x2_t)); }
; DI float bflo(unsigned w) { return __uint_as_float(w << 16); }
; DI float bfhi(unsigned w) { return __uint_as_float(w & 0xffff0000u); }
; DI float silu(float x) { return x * frcp(1.0f + fexp2(-x * LOG2E)); }
; DI float xsum32(float x) { const unsigned u = __float_as_uint(x); const auto r = __builtin_amdgcn_permlane32_swap(u, u, false, false); return __uint_as_float(r[0]) + __uint_as_float(r[1]); }
; DI void dsa_unit(const Params& p, int l, int b, int g32, LAS unsigned char* lds) {
;     ...
;     lsum = xsum32(lsum);
;     if (r < 4) {
;       const float inv = 1.0f / lsum;
; #pragma unroll
;       for (int et = 0; et < 2; ++et)
; #pragma unroll
;         for (int g = 0; g < 4; ++g) {
;           const int e0 = r * 64 + 32 * et + 8 * g + 4 * h;
;           const u32x2 gw = *(const u32x2*)(proj + tq * NP + C_GA + e0);
;           u32x2 ow; ow.x = pk2(o[et][4 * g] * inv * silu(bflo(gw.x)), o[et][4 * g + 1] * inv * silu(bfhi(gw.x))); ow.y = pk2(o[et][4 * g + 2] * inv * silu(bflo(gw.y)), o[et][4 * g + 3] * inv * silu(bfhi(gw.y)));
;           *(u32x2*)(ybuf + tq * DM + e0) = ow;
;         }
;     }
.LBB0_961:
	s_or_b64 exec, exec, s[8:9]
	v_mad_u64_u32 v[34:35], s[2:3], v126, s85, 0
	v_mov_b32_e32 v0, v153
	v_mad_i32_i24 v35, v111, s85, v35
	v_mov_b32_e32 v127, v111
	v_permlane32_swap_b32_e32 v153, v0
	s_and_saveexec_b64 s[8:9], s[6:7]
	s_cbranch_execz .LBB0_897
	v_add_f32_e32 v0, v153, v0
	v_div_scale_f32 v36, s[2:3], v0, v0, 1.0
	v_rcp_f32_e32 v37, v36
	v_lshl_add_u64 v[34:35], v[120:121], 0, v[34:35]
	v_fma_f32 v38, -v36, v37, 1.0
	v_fmac_f32_e32 v37, v38, v37
	v_div_scale_f32 v38, vcc, 1.0, v0, 1.0
	v_mul_f32_e32 v39, v38, v37
	v_fma_f32 v40, -v36, v39, v38
	v_fmac_f32_e32 v39, v40, v37
	v_fma_f32 v36, -v36, v39, v38
	v_div_fmas_f32 v36, v36, v37, v39
	v_div_fixup_f32 v0, v36, v0, 1.0
	v_lshlrev_b64 v[36:37], 11, v[126:127]
	s_mul_i32 s3, s28, 0xc00
	v_lshl_add_u64 v[36:37], v[124:125], 0, v[36:37]
	v_readfirstlane_b32 s10, v34
	v_readfirstlane_b32 s11, v35
	v_readfirstlane_b32 s12, v36
	v_readfirstlane_b32 s13, v37
	v_lshl_add_u32 v34, v128, 8, v129
	v_and_b32_e32 v35, 32, v123
	v_lshrrev_b32_e32 v35, 1, v35
	v_add3_u32 v34, v34, v35, s3
	v_lshl_add_u32 v36, v128, 2, v129
	v_add_u32_e32 v36, s3, v36
	ds_write_b32 v36, v0 offset:1024
	ds_write_b128 v34, v[18:21]
	ds_write_b128 v34, v[22:25] offset:32
	ds_write_b128 v34, v[26:29] offset:64
	ds_write_b128 v34, v[30:33] offset:96
	ds_write_b128 v34, v[2:5] offset:128
	ds_write_b128 v34, v[6:9] offset:160
	ds_write_b128 v34, v[10:13] offset:192
	ds_write_b128 v34, v[14:17] offset:224
	s_mov_b64 exec, -1
	v_lshlrev_b32_e32 v35, 3, v123
	v_lshl_add_u32 v36, v123, 4, v129
	global_load_dwordx2 v[66:67], v35, s[10:11] offset:1920
	v_add_u32_e32 v36, s3, v36
	v_lshrrev_b32_e32 v37, 4, v123
	v_lshl_add_u32 v37, v37, 2, v129
	v_add_u32_e32 v37, s3, v37
	s_waitcnt lgkmcnt(0)
	ds_read_b128 v[18:21], v36
	ds_read_b32 v0, v37 offset:1024
	s_waitcnt vmcnt(0)
	v_lshlrev_b32_e32 v28, 16, v66
	v_and_b32_e32 v29, 0xffff0000, v66
	v_lshlrev_b32_e32 v30, 16, v67
	v_and_b32_e32 v31, 0xffff0000, v67
	v_mul_f32_e32 v22, 0xbfb8aa3b, v28
	v_mul_f32_e32 v23, 0xbfb8aa3b, v29
	v_mul_f32_e32 v24, 0xbfb8aa3b, v30
	v_mul_f32_e32 v25, 0xbfb8aa3b, v31
	v_exp_f32_e32 v22, v22
	v_exp_f32_e32 v23, v23
	v_exp_f32_e32 v24, v24
	v_exp_f32_e32 v25, v25
	v_add_f32_e32 v22, 1.0, v22
	v_add_f32_e32 v23, 1.0, v23
	v_add_f32_e32 v24, 1.0, v24
	v_add_f32_e32 v25, 1.0, v25
	v_rcp_f32_e32 v22, v22
	v_rcp_f32_e32 v23, v23
	v_rcp_f32_e32 v24, v24
	v_rcp_f32_e32 v25, v25
	s_waitcnt lgkmcnt(0)
	v_pk_mul_f32 v[18:19], v[18:19], v[0:1] op_sel_hi:[1,0]
	v_pk_mul_f32 v[20:21], v[20:21], v[0:1] op_sel_hi:[1,0]
	v_pk_mul_f32 v[28:29], v[22:23], v[28:29]
	v_pk_mul_f32 v[30:31], v[24:25], v[30:31]
	s_nop 0
	v_pk_mul_f32 v[18:19], v[18:19], v[28:29]
	v_pk_mul_f32 v[20:21], v[20:21], v[30:31]
	s_nop 0
	v_cvt_pk_bf16_f32 v22, v18, v19
	v_cvt_pk_bf16_f32 v23, v20, v21
	global_store_dwordx2 v35, v[22:23], s[12:13]
	s_branch .LBB0_897
	s_nop 0
